# v25: v24 + l0 q/kv up-projection phase write-through with flat barrier
# speedup vs baseline: 1.0109x; 1.0053x over previous
.LBB0_833:
	s_cmp_lt_i32 s59, 6
	s_waitcnt vmcnt(0)
	s_barrier
	s_cbranch_scc1 .LBB0_887
	s_waitcnt vmcnt(0)
	s_barrier
	s_and_saveexec_b64 s[2:3], s[0:1]
	s_cbranch_execz .LBB0_886
	s_waitcnt vmcnt(0) lgkmcnt(0)
	v_mov_b32_e32 v241, 0
	v_lshlrev_b32_e64 v254, 8, s31
	v_mov_b32_e32 v247, 1
	v_mov_b32_e32 v246, 0x3600
	global_atomic_add v248, v246, v247, s[60:61] sc0
